# GQA fast loop: next-tile K fragments read before the step barrier (K staged one tile further ahead), restage ds_writes moved into the QK region
# speedup vs baseline: 1.0180x; 1.0080x over previous
; template <int DK>
; __device__ __forceinline__ void attn_unit(LAS unsigned char* lds, const bf16_t* Qp, int qpitch, const bf16_t* Kp, int kpitch, const bf16_t* Vp, int vpitch, bf16_t* Op, int nt) {
;     ...
;     int tid_ = threadIdx.x; asm volatile("" : "+v"(tid_));
;     const int tid = tid_, lane = tid & 63, wid = tid >> 6, r32 = lane & 31, hi = lane >> 5;
;     bf16x8 qf[NDS];
;     {
;         const bf16_t* qrow = Qp + (size_t)(wid * 32 + r32) * qpitch + 8 * hi;
; #pragma unroll
;         for (int ds = 0; ds < NDS; ++ds) qf[ds] = *(const bf16x8*)(qrow + ds * 16);
;     }
;     const int kr0 = tid / KCH, kc0 = tid % KCH;
;     const int c1 = tid + NTHREADS; const bool has1 = (DK == 96) && (c1 < 64 * KCH);
;     const int kr1 = has1 ? c1 / KCH : 0, kc1 = has1 ? c1 % KCH : 0;
;     const int vd = tid >> 3, vc = tid & 7;
;     const bf16_t* kg0 = Kp + (size_t)kr0 * kpitch + kc0 * 8;
;     const bf16_t* kg1 = Kp + (size_t)kr1 * kpitch + kc1 * 8;
;     const bf16_t* vg = Vp + (size_t)vd * vpitch + vc * 8;
;     const size_t kstep = (size_t)64 * kpitch, vstep = (size_t)64 * vpitch;
;     const int kl0 = kr0 * KSTR + kc0 * 16, kl1 = kr1 * KSTR + kc1 * 16, vl = vd * VSTR + vc * 16;
;     const int aoffk = r32 * KSTR + hi * 16;
;     const int aoffv = (4 * hi + ((lane & 15) >> 2)) * VSTR + (((lane >> 4) & 1) * 16 + (lane & 3) * 4) * 2;
;     {
;         const u32x4 a0 = *(const u32x4*)kg0, b0 = *(const u32x4*)(kg0 + kstep), v0 = *(const u32x4*)vg;
;         u32x4 a1 = {0u, 0u, 0u, 0u}, b1 = {0u, 0u, 0u, 0u};
;         if (has1) { a1 = *(const u32x4*)kg1; b1 = *(const u32x4*)(kg1 + kstep); }
;         *(LAS u32x4*)(lds + kl0) = a0; *(LAS u32x4*)(lds + KBUF + kl0) = b0; *(LAS u32x4*)(lds + 2 * KBUF + vl) = v0;
;         if (has1) { *(LAS u32x4*)(lds + kl1) = a1; *(LAS u32x4*)(lds + KBUF + kl1) = b1; }
;     }
;     u32x4 rkA0 = {0u, 0u, 0u, 0u}, rkA1 = {0u, 0u, 0u, 0u}, rvA = {0u, 0u, 0u, 0u}, rkB0, rkB1 = {0u, 0u, 0u, 0u}, rvB;
;     rkB0 = *(const u32x4*)(kg0 + 2 * kstep); if (has1) rkB1 = *(const u32x4*)(kg1 + 2 * kstep); rvB = *(const u32x4*)(vg + vstep);
;     __syncthreads();
;     f32x16 o0, o1, cA0, cA1, cB0, cB1;
; #pragma unroll
;     for (int i = 0; i < 16; ++i) { o0[i] = 0.f; o1[i] = 0.f; cA0[i] = 0.f; cA1[i] = 0.f; }
; #pragma unroll
;     for (int ds = 0; ds < NDS; ++ds) {
;         const bf16x8 a0 = *(const LAS bf16x8*)(lds + aoffk + ds * 32);
.LBB0_777:
	s_and_b64 vcc, exec, s[16:17]
	s_cbranch_vccz .LBB0_740
	v_mov_b32_e32 v8, v174
	s_movk_i32 s16, 0xffe0
	v_ashrrev_i32_e32 v0, 1, v8
	v_bfe_u32 v9, v8, 5, 1
	v_bfi_b32 v114, s16, v0, v8
	v_mov_b64_e32 v[0:1], s[14:15]
	s_movk_i32 s14, 0x300
	v_mad_i64_i32 v[0:1], s[14:15], v114, s14, v[0:1]
	v_lshlrev_b32_e32 v96, 4, v9
	v_lshl_add_u64 v[0:1], v[0:1], 0, v[96:97]
	global_load_dwordx4 v[76:79], v[0:1], off
	global_load_dwordx4 v[72:75], v[0:1], off offset:32
	global_load_dwordx4 v[68:71], v[0:1], off offset:64
	global_load_dwordx4 v[64:67], v[0:1], off offset:96
	v_ashrrev_i32_e32 v0, 31, v8
	v_lshrrev_b32_e32 v0, 29, v0
	v_add_u32_e32 v1, v8, v0
	v_ashrrev_i32_e32 v0, 3, v1
	v_and_b32_e32 v1, -8, v1
	v_sub_u32_e32 v10, v8, v1
	v_ashrrev_i32_e32 v2, 3, v8
	v_ashrrev_i32_e32 v1, 31, v0
	v_lshlrev_b32_e32 v6, 3, v10
	v_lshlrev_b64 v[36:37], 8, v[0:1]
	v_ashrrev_i32_e32 v7, 31, v6
	v_ashrrev_i32_e32 v3, 31, v2
	v_lshl_add_u64 v[4:5], s[12:13], 0, v[36:37]
	v_lshlrev_b64 v[38:39], 1, v[6:7]
	v_lshlrev_b64 v[32:33], 8, v[2:3]
	v_lshlrev_b32_e32 v1, 4, v8
	v_lshl_add_u64 v[120:121], v[4:5], 0, v[38:39]
	v_lshl_add_u64 v[4:5], s[10:11], 0, v[32:33]
	v_and_b32_e32 v34, 0x70, v1
	v_mov_b32_e32 v35, v97
	s_movk_i32 s12, 0x90
	s_movk_i32 s10, 0xc0
	v_mul_lo_u32 v0, v0, s12
	v_mad_u64_u32 v[12:13], s[10:11], v2, s10, v[34:35]
	v_lshl_add_u32 v15, v10, 4, v0
	v_bfe_u32 v0, v8, 2, 2
	s_movk_i32 s10, 0x4000
	v_lshl_add_u64 v[118:119], v[4:5], 0, v[34:35]
	v_lshl_or_b32 v13, v9, 2, v0
	v_and_b32_e32 v0, 16, v8
	v_lshlrev_b32_e32 v1, 2, v8
	v_add_co_u32_e32 v4, vcc, s10, v120
	v_and_or_b32 v48, v1, 12, v0
	global_load_dwordx4 v[0:3], v[120:121], off
	v_addc_co_u32_e32 v5, vcc, 0, v121, vcc
	v_and_b32_e32 v14, 31, v8
	v_lshlrev_b32_e32 v116, 3, v9
	global_load_dwordx4 v[4:7], v[4:5], off
	s_nop 0
	global_load_dwordx4 v[8:11], v[118:119], off
	v_add_u32_e32 v130, 0, v15
	s_mov_b32 s11, 0x8000
	v_add_u32_e32 v117, 0, v12
	v_mul_u32_u24_e32 v49, 0xc0, v13
	v_mov_b32_e32 v172, 0
	v_ashrrev_i32_e32 v115, 31, v114
	s_waitcnt vmcnt(2)
	ds_write_b128 v130, v[0:3]
	s_waitcnt vmcnt(1)
	ds_write_b128 v130, v[4:7] offset:13312
	v_add_co_u32_e32 v0, vcc, s11, v120
	s_waitcnt vmcnt(0)
	ds_write_b128 v117, v[8:11] offset:26624
	v_addc_co_u32_e32 v1, vcc, 0, v121, vcc
	global_load_dwordx4 v[80:83], v[0:1], off
	v_add_co_u32_e32 v0, vcc, s10, v118
	s_mov_b32 s10, -2
	s_nop 0
	v_addc_co_u32_e32 v1, vcc, 0, v119, vcc
	global_load_dwordx4 v[84:87], v[0:1], off
	v_mad_u32_u24 v0, v14, s12, v96
	v_add_u32_e32 v131, 0, v0
	s_waitcnt lgkmcnt(0)
	s_barrier
	ds_read_b128 v[16:19], v131 offset:4608
	ds_read_b128 v[0:3], v131
	ds_read_b128 v[40:43], v131 offset:32
	s_waitcnt lgkmcnt(1)
	v_mfma_f32_32x32x16_bf16 v[0:15], v[0:3], v[76:79], 0
	ds_read_b128 v[44:47], v131 offset:4640
	v_mfma_f32_32x32x16_bf16 v[16:31], v[16:19], v[76:79], 0
	s_waitcnt lgkmcnt(1)
	v_mfma_f32_32x32x16_bf16 v[0:15], v[40:43], v[72:75], v[0:15]
	s_waitcnt lgkmcnt(0)
	v_mfma_f32_32x32x16_bf16 v[16:31], v[44:47], v[72:75], v[16:31]
	ds_read_b128 v[40:43], v131 offset:64
	ds_read_b128 v[44:47], v131 offset:4672
	s_waitcnt lgkmcnt(1)
	v_mfma_f32_32x32x16_bf16 v[0:15], v[40:43], v[68:71], v[0:15]
	s_waitcnt lgkmcnt(0)
	v_mfma_f32_32x32x16_bf16 v[16:31], v[44:47], v[68:71], v[16:31]
	ds_read_b128 v[40:43], v131 offset:96
	ds_read_b128 v[44:47], v131 offset:4704
	s_waitcnt lgkmcnt(0)
	s_barrier
	v_mfma_f32_32x32x16_bf16 v[0:15], v[40:43], v[64:67], v[0:15]
	v_mfma_f32_32x32x16_bf16 v[16:31], v[44:47], v[64:67], v[16:31]
	s_nop 10
	v_exp_f32_e32 v146, v0
	v_lshl_or_b32 v0, v48, 1, v49
	v_exp_f32_e32 v148, v1
	v_add_u32_e32 v96, 0, v0
	v_lshl_add_u64 v[0:1], s[70:71], 0, v[36:37]
	v_exp_f32_e32 v158, v2
	v_exp_f32_e32 v159, v3
	v_exp_f32_e32 v132, v16
	v_exp_f32_e32 v133, v17
	v_exp_f32_e32 v134, v18
	v_exp_f32_e32 v135, v19
	v_exp_f32_e32 v160, v4
	v_exp_f32_e32 v136, v20
	v_exp_f32_e32 v162, v5
	v_exp_f32_e32 v137, v21
	v_exp_f32_e32 v164, v6
	v_exp_f32_e32 v139, v22
	v_exp_f32_e32 v166, v7
	v_exp_f32_e32 v141, v23
	v_exp_f32_e32 v161, v8
	v_exp_f32_e32 v138, v24
	v_exp_f32_e32 v163, v9
	v_exp_f32_e32 v140, v25
	v_exp_f32_e32 v165, v10
	v_exp_f32_e32 v142, v26
	v_exp_f32_e32 v168, v11
	v_exp_f32_e32 v143, v27
	v_exp_f32_e32 v167, v12
	v_exp_f32_e32 v144, v28
	v_exp_f32_e32 v169, v13
	v_exp_f32_e32 v145, v29
	v_exp_f32_e32 v170, v14
	v_exp_f32_e32 v147, v30
	v_exp_f32_e32 v171, v15
	v_exp_f32_e32 v149, v31
	v_lshl_add_u64 v[0:1], v[0:1], 0, v[38:39]
	v_lshl_add_u64 v[122:123], s[50:51], 0, v[0:1]
	v_lshl_add_u64 v[0:1], s[70:71], 0, v[32:33]
	v_lshl_add_u64 v[0:1], v[0:1], 0, v[34:35]
	v_lshl_add_u64 v[124:125], s[50:51], 0, v[0:1]
	v_mov_b32_e32 v0, 0
	v_mov_b32_e32 v1, v172
	v_mov_b32_e32 v2, v172
	v_mov_b32_e32 v3, v172
	v_mov_b32_e32 v4, v172
	v_mov_b32_e32 v5, v172
	v_mov_b32_e32 v6, v172
	v_mov_b32_e32 v7, v172
	v_mov_b32_e32 v8, v172
	v_mov_b32_e32 v9, v172
	v_mov_b32_e32 v10, v172
	v_mov_b32_e32 v11, v172
	v_mov_b32_e32 v12, v172
	v_mov_b32_e32 v13, v172
	v_mov_b32_e32 v14, v172
	v_mov_b32_e32 v15, v172
	v_mov_b32_e32 v16, 0
	v_mov_b32_e32 v17, v172
	v_mov_b32_e32 v18, v172
	v_mov_b32_e32 v19, v172
	v_mov_b32_e32 v20, v172
	v_mov_b32_e32 v21, v172
	v_mov_b32_e32 v22, v172
	v_mov_b32_e32 v23, v172
	v_mov_b32_e32 v24, v172
	v_mov_b32_e32 v25, v172
	v_mov_b32_e32 v26, v172
	v_mov_b32_e32 v27, v172
	v_mov_b32_e32 v28, v172
	v_mov_b32_e32 v29, v172
	v_mov_b32_e32 v30, v172
	v_mov_b32_e32 v31, v172
	s_waitcnt vmcnt(0)
	ds_write_b128 v130, v[80:83]
	ds_read_b128 v[216:219], v131 offset:17920
	ds_read_b128 v[220:223], v131 offset:13312
	ds_read_b128 v[224:227], v131 offset:13344
	ds_read_b128 v[228:231], v131 offset:17952
	ds_read_b128 v[236:239], v131 offset:13376
	ds_read_b128 v[240:243], v131 offset:17984
	ds_read_b128 v[244:247], v131 offset:13408
	ds_read_b128 v[248:251], v131 offset:18016
	v_add_co_u32_e32 v32, vcc, 0xc000, v120
	s_nop 1
	v_addc_co_u32_e32 v33, vcc, 0, v121, vcc
	s_waitcnt lgkmcnt(8)
	global_load_dwordx4 v[80:83], v[32:33], off
	v_add_co_u32_e32 v32, vcc, 0x4000, v118
	s_nop 1
	v_addc_co_u32_e32 v33, vcc, 0, v119, vcc
	global_load_dwordx4 v[84:87], v[32:33], off
	s_waitcnt lgkmcnt(0)
	s_barrier
; #define LAS __attribute__((address_space(3)))
; template <int DK, int PAR, bool HASNEXT, bool LDK, bool LDV, bool STK> ...
;     ...
;     LAS unsigned char* Kb = lds + ((PAR ^ 1) * A::KBUF);
;     LAS unsigned char* Vb = lds + 2 * A::KBUF + PAR * A::VBUF;
;     __builtin_amdgcn_s_setprio(1);
;     if (LDK) { ldk0 = *(const u32x4*)(kg0 + (size_t)(t + 3) * kstep); if (has1) ldk1 = *(const u32x4*)(kg1 + (size_t)(t + 3) * kstep); }
;     if (LDV) ldv = *(const u32x4*)(vg + (size_t)(t + 2) * vstep);
;     bf16x8 kf[A::NDS][2];
;     if (HASNEXT) {
; #pragma unroll
;         for (int ds = 0; ds < A::NDS; ++ds) {
;             kf[ds][0] = *(const LAS bf16x8*)(Kb + aoffk + ds * 32);
;             kf[ds][1] = *(const LAS bf16x8*)(Kb + aoffk + 32 * A::KSTR + ds * 32);
;         }
;     }
;     s16x4 vlo[4][2], vhi[4][2];
; #pragma unroll
;     for (int j = 0; j < 2; ++j) {
;         vlo[j][0] = vtr(Vb + aoffv + j * 16 * A::VSTR); vhi[j][0] = vtr(Vb + aoffv + (j * 16 + 8) * A::VSTR);
;         vlo[j][1] = vtr(Vb + aoffv + j * 16 * A::VSTR + 64); vhi[j][1] = vtr(Vb + aoffv + (j * 16 + 8) * A::VSTR + 64);
;     }
;     if (HASNEXT) {
;         f32x16 z;
; #pragma unroll
;         for (int i = 0; i < 16; ++i) z[i] = 0.f;
; #pragma unroll
;         for (int ds = 0; ds < A::NDS; ++ds) {
;             N0 = __builtin_amdgcn_mfma_f32_32x32x16_bf16(kf[ds][0], qf[ds], ds == 0 ? z : N0, 0, 0, 0);
;             N1 = __builtin_amdgcn_mfma_f32_32x32x16_bf16(kf[ds][1], qf[ds], ds == 0 ? z : N1, 0, 0, 0);
;         }
;     }
; #pragma unroll
;     for (int i = 0; i < 16; ++i) { l += C0[i]; l += C1[i]; }
;     bf16x8 pb[4];
;     { u32x4 w;
;       w.x = pk2(C0[0], C0[1]); w.y = pk2(C0[2], C0[3]); w.z = pk2(C0[4], C0[5]); w.w = pk2(C0[6], C0[7]); pb[0] = __builtin_bit_cast(bf16x8, w);
;       w.x = pk2(C0[8], C0[9]); w.y = pk2(C0[10], C0[11]); w.z = pk2(C0[12], C0[13]); w.w = pk2(C0[14], C0[15]); pb[1] = __builtin_bit_cast(bf16x8, w);
;       w.x = pk2(C1[0], C1[1]); w.y = pk2(C1[2], C1[3]); w.z = pk2(C1[4], C1[5]); w.w = pk2(C1[6], C1[7]); pb[2] = __builtin_bit_cast(bf16x8, w);
;       w.x = pk2(C1[8], C1[9]); w.y = pk2(C1[10], C1[11]); w.z = pk2(C1[12], C1[13]); w.w = pk2(C1[14], C1[15]); pb[3] = __builtin_bit_cast(bf16x8, w); }
;     if (HASNEXT) {
;         constexpr int VPER = (DK == 64) ? 6 : 4;
; #pragma unroll
.LBB0_779:
	s_setprio 1
	s_mov_b32 s11, 0x23a30000
	ds_read_b64_tr_b16 v[110:111], v96 offset:26624
	v_mfma_f32_32x32x16_bf16 v[48:63], v[216:219], v[76:79], 0
	v_lshl_add_u64 v[126:127], v[122:123], 0, s[8:9]
	v_add_co_u32_e32 v32, vcc, s11, v126
	v_lshl_add_u64 v[128:129], v[124:125], 0, s[8:9]
	s_nop 0
	v_addc_co_u32_e32 v33, vcc, 0, v127, vcc
	s_mov_b32 s11, 0x24aa8000
	global_load_dwordx4 v[88:91], v[32:33], off
	v_add_co_u32_e32 v32, vcc, s11, v128
	ds_read_b64_tr_b16 v[112:113], v96 offset:28160
	s_nop 0
	v_addc_co_u32_e32 v33, vcc, 0, v129, vcc
	global_load_dwordx4 v[92:95], v[32:33], off
	v_mfma_f32_32x32x16_bf16 v[32:47], v[220:223], v[76:79], 0
	v_add_f32_e32 v150, v146, v172
	v_add_f32_e32 v150, v132, v150
	v_add_f32_e32 v150, v148, v150
	v_add_f32_e32 v150, v133, v150
	v_add_f32_e32 v150, v158, v150
	v_add_f32_e32 v150, v134, v150
	ds_read_b64_tr_b16 v[106:107], v96 offset:26688
	v_mfma_f32_32x32x16_bf16 v[32:47], v[224:227], v[72:75], v[32:47]
	v_add_f32_e32 v150, v159, v150
	v_add_f32_e32 v150, v135, v150
	v_add_f32_e32 v150, v160, v150
	v_add_f32_e32 v150, v136, v150
	v_add_f32_e32 v150, v162, v150
	v_add_f32_e32 v150, v137, v150
	ds_read_b64_tr_b16 v[108:109], v96 offset:28224
	v_mfma_f32_32x32x16_bf16 v[48:63], v[228:231], v[72:75], v[48:63]
	s_waitcnt vmcnt(3)
	ds_write_b128 v130, v[80:83] offset:13312
	s_waitcnt vmcnt(2)
	ds_write_b128 v117, v[84:87] offset:38912
	v_add_f32_e32 v150, v164, v150
	v_add_f32_e32 v150, v139, v150
	v_add_f32_e32 v150, v166, v150
	v_add_f32_e32 v150, v141, v150
	v_add_f32_e32 v150, v161, v150
	v_add_f32_e32 v150, v138, v150
	ds_read_b64_tr_b16 v[102:103], v96 offset:29696
	v_mfma_f32_32x32x16_bf16 v[32:47], v[236:239], v[68:71], v[32:47]
	v_add_f32_e32 v150, v163, v150
	v_add_f32_e32 v150, v140, v150
	v_add_f32_e32 v150, v165, v150
	v_add_f32_e32 v150, v142, v150
	v_add_f32_e32 v150, v168, v150
	v_add_f32_e32 v150, v143, v150
	ds_read_b64_tr_b16 v[104:105], v96 offset:31232
	v_mfma_f32_32x32x16_bf16 v[48:63], v[240:243], v[68:71], v[48:63]
	v_add_f32_e32 v150, v167, v150
	v_add_f32_e32 v150, v144, v150
	v_add_f32_e32 v150, v169, v150
	v_add_f32_e32 v150, v145, v150
	ds_read_b64_tr_b16 v[98:99], v96 offset:29760
	ds_read_b64_tr_b16 v[100:101], v96 offset:31296
	v_add_f32_e32 v150, v170, v150
	v_add_f32_e32 v150, v147, v150
	v_mfma_f32_32x32x16_bf16 v[32:47], v[244:247], v[64:67], v[32:47]
	v_add_f32_e32 v150, v171, v150
	v_add_f32_e32 v152, v149, v150
	v_cvt_pk_bf16_f32 v182, v146, v148
	v_cvt_pk_bf16_f32 v183, v158, v159
	v_cvt_pk_bf16_f32 v184, v160, v162
	v_cvt_pk_bf16_f32 v185, v164, v166
	v_mfma_f32_32x32x16_bf16 v[48:63], v[248:251], v[64:67], v[48:63]
	v_cvt_pk_bf16_f32 v158, v161, v163
	v_cvt_pk_bf16_f32 v159, v165, v168
	v_cvt_pk_bf16_f32 v160, v167, v169
	v_cvt_pk_bf16_f32 v161, v170, v171
	v_cvt_pk_bf16_f32 v132, v132, v133
	v_cvt_pk_bf16_f32 v133, v134, v135
	v_cvt_pk_bf16_f32 v134, v136, v137
	v_cvt_pk_bf16_f32 v135, v139, v141
	v_cvt_pk_bf16_f32 v136, v138, v140
	v_cvt_pk_bf16_f32 v137, v142, v143
	v_cvt_pk_bf16_f32 v138, v144, v145
	v_cvt_pk_bf16_f32 v139, v147, v149
	s_waitcnt lgkmcnt(8)
	v_mfma_f32_32x32x16_bf16 v[16:31], v[110:113], v[182:185], v[16:31]
	ds_read_b64_tr_b16 v[110:111], v96 offset:32832
	ds_read_b64_tr_b16 v[112:113], v96 offset:34368
	ds_read_b64_tr_b16 v[140:141], v96 offset:35904
	ds_read_b64_tr_b16 v[142:143], v96 offset:37440
	v_exp_f32_e32 v162, v51
	v_exp_f32_e32 v163, v36
	v_exp_f32_e32 v164, v52
	s_waitcnt lgkmcnt(10)
	v_mfma_f32_32x32x16_bf16 v[0:15], v[106:109], v[182:185], v[0:15]
	ds_read_b64_tr_b16 v[106:107], v96 offset:32768
	ds_read_b64_tr_b16 v[108:109], v96 offset:34304
	v_exp_f32_e32 v165, v37
	v_exp_f32_e32 v166, v53
	v_exp_f32_e32 v167, v38
	v_exp_f32_e32 v168, v54
	v_exp_f32_e32 v169, v39
	s_waitcnt lgkmcnt(8)
	v_mfma_f32_32x32x16_bf16 v[16:31], v[102:105], v[158:161], v[16:31]
	ds_read_b64_tr_b16 v[102:103], v96 offset:35840
	ds_read_b64_tr_b16 v[104:105], v96 offset:37376
	v_exp_f32_e32 v170, v55
	v_exp_f32_e32 v171, v40
	v_exp_f32_e32 v153, v32
	v_exp_f32_e32 v154, v48
	v_exp_f32_e32 v155, v33
	s_waitcnt lgkmcnt(8)
	v_mfma_f32_32x32x16_bf16 v[0:15], v[98:101], v[158:161], v[0:15]
	ds_read_b128 v[216:219], v131 offset:4608
	ds_read_b128 v[220:223], v131
	v_exp_f32_e32 v158, v49
	v_exp_f32_e32 v159, v34
	v_exp_f32_e32 v160, v50
	v_exp_f32_e32 v161, v35
	v_exp_f32_e32 v173, v56
	v_exp_f32_e32 v180, v41
	v_exp_f32_e32 v181, v57
	s_waitcnt lgkmcnt(4)
	v_mfma_f32_32x32x16_bf16 v[16:31], v[106:109], v[132:135], v[16:31]
	ds_read_b128 v[224:227], v131 offset:32
	ds_read_b128 v[228:231], v131 offset:64
	v_exp_f32_e32 v182, v42
	v_exp_f32_e32 v183, v58
	v_exp_f32_e32 v184, v43
	v_exp_f32_e32 v185, v59
	v_exp_f32_e32 v186, v44
	v_exp_f32_e32 v187, v60
	v_exp_f32_e32 v188, v45
	v_mfma_f32_32x32x16_bf16 v[0:15], v[110:113], v[132:135], v[0:15]
	ds_read_b128 v[236:239], v131 offset:96
	ds_read_b128 v[240:243], v131 offset:4640
	v_exp_f32_e32 v189, v61
	v_exp_f32_e32 v190, v46
	v_exp_f32_e32 v191, v62
	v_exp_f32_e32 v192, v47
	v_exp_f32_e32 v193, v63
	s_waitcnt lgkmcnt(6)
	v_mfma_f32_32x32x16_bf16 v[16:31], v[102:105], v[136:139], v[16:31]
	ds_read_b128 v[244:247], v131 offset:4672
	ds_read_b128 v[248:251], v131 offset:4704
	v_mfma_f32_32x32x16_bf16 v[0:15], v[140:143], v[136:139], v[0:15]
	s_setprio 0
	s_waitcnt lgkmcnt(0)
	s_barrier
; #define LAS __attribute__((address_space(3)))
; template <int DK, int PAR, bool HASNEXT, bool LDK, bool LDV, bool STK> ...
;     ...
;     LAS unsigned char* Kb = lds + ((PAR ^ 1) * A::KBUF);
;     LAS unsigned char* Vb = lds + 2 * A::KBUF + PAR * A::VBUF;
;     __builtin_amdgcn_s_setprio(1);
;     if (LDK) { ldk0 = *(const u32x4*)(kg0 + (size_t)(t + 3) * kstep); if (has1) ldk1 = *(const u32x4*)(kg1 + (size_t)(t + 3) * kstep); }
;     if (LDV) ldv = *(const u32x4*)(vg + (size_t)(t + 2) * vstep);
;     bf16x8 kf[A::NDS][2];
;     if (HASNEXT) {
; #pragma unroll
;         for (int ds = 0; ds < A::NDS; ++ds) {
;             kf[ds][0] = *(const LAS bf16x8*)(Kb + aoffk + ds * 32);
;             kf[ds][1] = *(const LAS bf16x8*)(Kb + aoffk + 32 * A::KSTR + ds * 32);
;         }
;     }
;     s16x4 vlo[4][2], vhi[4][2];
; #pragma unroll
;     for (int j = 0; j < 2; ++j) {
;         vlo[j][0] = vtr(Vb + aoffv + j * 16 * A::VSTR); vhi[j][0] = vtr(Vb + aoffv + (j * 16 + 8) * A::VSTR);
;         vlo[j][1] = vtr(Vb + aoffv + j * 16 * A::VSTR + 64); vhi[j][1] = vtr(Vb + aoffv + (j * 16 + 8) * A::VSTR + 64);
;     }
;     if (HASNEXT) {
;         f32x16 z;
; #pragma unroll
;         for (int i = 0; i < 16; ++i) z[i] = 0.f;
; #pragma unroll
;         for (int ds = 0; ds < A::NDS; ++ds) {
;             N0 = __builtin_amdgcn_mfma_f32_32x32x16_bf16(kf[ds][0], qf[ds], ds == 0 ? z : N0, 0, 0, 0);
;             N1 = __builtin_amdgcn_mfma_f32_32x32x16_bf16(kf[ds][1], qf[ds], ds == 0 ? z : N1, 0, 0, 0);
;         }
;     }
; #pragma unroll
;     for (int i = 0; i < 16; ++i) { l += C0[i]; l += C1[i]; }
;     bf16x8 pb[4];
;     { u32x4 w;
;       w.x = pk2(C0[0], C0[1]); w.y = pk2(C0[2], C0[3]); w.z = pk2(C0[4], C0[5]); w.w = pk2(C0[6], C0[7]); pb[0] = __builtin_bit_cast(bf16x8, w);
;       w.x = pk2(C0[8], C0[9]); w.y = pk2(C0[10], C0[11]); w.z = pk2(C0[12], C0[13]); w.w = pk2(C0[14], C0[15]); pb[1] = __builtin_bit_cast(bf16x8, w);
;       w.x = pk2(C1[0], C1[1]); w.y = pk2(C1[2], C1[3]); w.z = pk2(C1[4], C1[5]); w.w = pk2(C1[6], C1[7]); pb[2] = __builtin_bit_cast(bf16x8, w);
;       w.x = pk2(C1[8], C1[9]); w.y = pk2(C1[10], C1[11]); w.z = pk2(C1[12], C1[13]); w.w = pk2(C1[14], C1[15]); pb[3] = __builtin_bit_cast(bf16x8, w); }
;     if (HASNEXT) {
;         constexpr int VPER = (DK == 64) ? 6 : 4;
; #pragma unroll
	s_setprio 1
	s_mov_b32 s11, 0x23a34000
	ds_read_b64_tr_b16 v[110:111], v96 offset:38912
	ds_read_b64_tr_b16 v[112:113], v96 offset:40448
	v_mfma_f32_32x32x16_bf16 v[48:63], v[216:219], v[76:79], 0
	v_add_co_u32_e32 v32, vcc, s11, v126
	s_mov_b32 s11, 0x24aac000
	s_nop 0
	v_addc_co_u32_e32 v33, vcc, 0, v127, vcc
	global_load_dwordx4 v[80:83], v[32:33], off
	v_add_co_u32_e32 v32, vcc, s11, v128
	ds_read_b64_tr_b16 v[106:107], v96 offset:38976
	s_nop 0
	v_addc_co_u32_e32 v33, vcc, 0, v129, vcc
	global_load_dwordx4 v[84:87], v[32:33], off
	v_mfma_f32_32x32x16_bf16 v[32:47], v[220:223], v[76:79], 0
	ds_read_b64_tr_b16 v[108:109], v96 offset:40512
	ds_read_b64_tr_b16 v[102:103], v96 offset:41984
	ds_read_b64_tr_b16 v[104:105], v96 offset:43520
	ds_read_b64_tr_b16 v[98:99], v96 offset:42048
	ds_read_b64_tr_b16 v[100:101], v96 offset:43584
	v_mfma_f32_32x32x16_bf16 v[32:47], v[224:227], v[72:75], v[32:47]
	v_mfma_f32_32x32x16_bf16 v[32:47], v[228:231], v[68:71], v[32:47]
	s_waitcnt vmcnt(3)
	ds_write_b128 v130, v[88:91]
	s_waitcnt vmcnt(2)
	ds_write_b128 v117, v[92:95] offset:26624
	v_mfma_f32_32x32x16_bf16 v[32:47], v[236:239], v[64:67], v[32:47]
	v_cvt_pk_bf16_f32 v144, v164, v166
	v_cvt_pk_bf16_f32 v145, v168, v170
	v_cvt_pk_bf16_f32 v136, v186, v188
	v_cvt_pk_bf16_f32 v137, v190, v192
	v_mfma_f32_32x32x16_bf16 v[48:63], v[240:243], v[72:75], v[48:63]
	v_cvt_pk_bf16_f32 v134, v171, v180
	v_cvt_pk_bf16_f32 v135, v182, v184
	v_mfma_f32_32x32x16_bf16 v[48:63], v[244:247], v[68:71], v[48:63]
	v_cvt_pk_bf16_f32 v142, v154, v158
	v_cvt_pk_bf16_f32 v143, v160, v162
	v_add_f32_e32 v126, v153, v152
	v_add_f32_e32 v126, v154, v126
	v_add_f32_e32 v126, v155, v126
	v_add_f32_e32 v126, v158, v126
	v_add_f32_e32 v126, v159, v126
	v_add_f32_e32 v126, v160, v126
	v_add_f32_e32 v126, v161, v126
	v_add_f32_e32 v126, v162, v126
	v_add_f32_e32 v126, v163, v126
	v_add_f32_e32 v126, v164, v126
	v_add_f32_e32 v126, v165, v126
	v_add_f32_e32 v126, v166, v126
	v_add_f32_e32 v126, v167, v126
	v_add_f32_e32 v126, v168, v126
	v_add_f32_e32 v126, v169, v126
	v_add_f32_e32 v126, v170, v126
	v_add_f32_e32 v126, v171, v126
	v_add_f32_e32 v126, v173, v126
	v_add_f32_e32 v126, v180, v126
	v_add_f32_e32 v126, v181, v126
	v_add_f32_e32 v126, v182, v126
	v_add_f32_e32 v126, v183, v126
	v_add_f32_e32 v126, v184, v126
	v_add_f32_e32 v126, v185, v126
	v_add_f32_e32 v126, v186, v126
	v_add_f32_e32 v126, v187, v126
	v_add_f32_e32 v126, v188, v126
	v_add_f32_e32 v126, v189, v126
	v_add_f32_e32 v126, v190, v126
	v_add_f32_e32 v126, v191, v126
	v_mfma_f32_32x32x16_bf16 v[48:63], v[248:251], v[64:67], v[48:63]
	v_add_f32_e32 v126, v192, v126
	v_add_f32_e32 v172, v193, v126
	v_cvt_pk_bf16_f32 v126, v153, v155
	v_cvt_pk_bf16_f32 v127, v159, v161
	v_cvt_pk_bf16_f32 v128, v163, v165
	v_cvt_pk_bf16_f32 v129, v167, v169
	v_cvt_pk_bf16_f32 v182, v173, v181
	v_cvt_pk_bf16_f32 v183, v183, v185
	v_cvt_pk_bf16_f32 v184, v187, v189
	v_cvt_pk_bf16_f32 v185, v191, v193
	s_waitcnt lgkmcnt(8)
	v_mfma_f32_32x32x16_bf16 v[16:31], v[110:113], v[126:129], v[16:31]
	ds_read_b64_tr_b16 v[110:111], v96 offset:45120
	ds_read_b64_tr_b16 v[112:113], v96 offset:46656
	v_exp_f32_e32 v146, v32
	v_exp_f32_e32 v132, v48
	v_exp_f32_e32 v148, v33
	v_exp_f32_e32 v133, v49
	v_exp_f32_e32 v158, v34
	s_waitcnt lgkmcnt(8)
	v_mfma_f32_32x32x16_bf16 v[0:15], v[106:109], v[126:129], v[0:15]
	ds_read_b64_tr_b16 v[106:107], v96 offset:45056
	ds_read_b64_tr_b16 v[108:109], v96 offset:46592
	ds_read_b64_tr_b16 v[126:127], v96 offset:48192
	ds_read_b64_tr_b16 v[128:129], v96 offset:49728
	v_exp_f32_e32 v159, v35
	v_exp_f32_e32 v160, v36
	v_exp_f32_e32 v162, v37
	s_waitcnt lgkmcnt(10)
	v_mfma_f32_32x32x16_bf16 v[16:31], v[102:105], v[134:137], v[16:31]
	ds_read_b64_tr_b16 v[102:103], v96 offset:48128
	ds_read_b64_tr_b16 v[104:105], v96 offset:49664
	v_exp_f32_e32 v164, v38
	v_exp_f32_e32 v139, v54
	v_exp_f32_e32 v166, v39
	v_exp_f32_e32 v141, v55
	v_exp_f32_e32 v161, v40
	s_waitcnt lgkmcnt(10)
	v_mfma_f32_32x32x16_bf16 v[0:15], v[98:101], v[134:137], v[0:15]
	ds_read_b128 v[216:219], v131 offset:17920
	ds_read_b128 v[220:223], v131 offset:13312
	v_exp_f32_e32 v134, v50
	v_exp_f32_e32 v135, v51
	v_exp_f32_e32 v136, v52
	v_exp_f32_e32 v137, v53
	v_exp_f32_e32 v138, v56
	v_exp_f32_e32 v163, v41
	v_exp_f32_e32 v140, v57
	s_waitcnt lgkmcnt(6)
	v_mfma_f32_32x32x16_bf16 v[16:31], v[106:109], v[142:145], v[16:31]
	ds_read_b128 v[224:227], v131 offset:13344
	ds_read_b128 v[228:231], v131 offset:17952
	v_exp_f32_e32 v165, v42
	v_exp_f32_e32 v168, v43
	v_exp_f32_e32 v167, v44
	v_exp_f32_e32 v169, v45
	v_exp_f32_e32 v170, v46
	v_exp_f32_e32 v147, v62
	v_exp_f32_e32 v171, v47
	v_mfma_f32_32x32x16_bf16 v[0:15], v[110:113], v[142:145], v[0:15]
	ds_read_b128 v[236:239], v131 offset:13376
	ds_read_b128 v[240:243], v131 offset:17984
	v_exp_f32_e32 v142, v58
	v_exp_f32_e32 v143, v59
	v_exp_f32_e32 v144, v60
	v_exp_f32_e32 v145, v61
	v_exp_f32_e32 v149, v63
	s_waitcnt lgkmcnt(6)
	v_mfma_f32_32x32x16_bf16 v[16:31], v[102:105], v[182:185], v[16:31]
	ds_read_b128 v[244:247], v131 offset:13408
	ds_read_b128 v[248:251], v131 offset:18016
	v_mfma_f32_32x32x16_bf16 v[0:15], v[126:129], v[182:185], v[0:15]
	s_setprio 0
	s_waitcnt lgkmcnt(0)
	s_barrier
	s_add_i32 s10, s10, 2
	v_lshl_add_u64 v[122:123], v[122:123], 0, s[34:35]
	s_cmpk_lt_u32 s10, 0x7e
	v_lshl_add_u64 v[124:125], v[124:125], 0, s[34:35]
	s_cbranch_scc1 .LBB0_779
; #define LAS __attribute__((address_space(3)))
; template <int DK, int PAR, bool HASNEXT, bool LDK, bool LDV, bool STK> ...
;     ...
;     LAS unsigned char* Kb = lds + ((PAR ^ 1) * A::KBUF);
;     LAS unsigned char* Vb = lds + 2 * A::KBUF + PAR * A::VBUF;
;     __builtin_amdgcn_s_setprio(1);
;     if (LDK) { ldk0 = *(const u32x4*)(kg0 + (size_t)(t + 3) * kstep); if (has1) ldk1 = *(const u32x4*)(kg1 + (size_t)(t + 3) * kstep); }
;     if (LDV) ldv = *(const u32x4*)(vg + (size_t)(t + 2) * vstep);
;     bf16x8 kf[A::NDS][2];
;     if (HASNEXT) {
; #pragma unroll
;         for (int ds = 0; ds < A::NDS; ++ds) {
;             kf[ds][0] = *(const LAS bf16x8*)(Kb + aoffk + ds * 32);
;             kf[ds][1] = *(const LAS bf16x8*)(Kb + aoffk + 32 * A::KSTR + ds * 32);
;         }
;     }
;     s16x4 vlo[4][2], vhi[4][2];
; #pragma unroll
;     for (int j = 0; j < 2; ++j) {
;         vlo[j][0] = vtr(Vb + aoffv + j * 16 * A::VSTR); vhi[j][0] = vtr(Vb + aoffv + (j * 16 + 8) * A::VSTR);
;         vlo[j][1] = vtr(Vb + aoffv + j * 16 * A::VSTR + 64); vhi[j][1] = vtr(Vb + aoffv + (j * 16 + 8) * A::VSTR + 64);
;     }
;     if (HASNEXT) {
;         f32x16 z;
; #pragma unroll
;         for (int i = 0; i < 16; ++i) z[i] = 0.f;
; #pragma unroll
;         for (int ds = 0; ds < A::NDS; ++ds) {
;             N0 = __builtin_amdgcn_mfma_f32_32x32x16_bf16(kf[ds][0], qf[ds], ds == 0 ? z : N0, 0, 0, 0);
;             N1 = __builtin_amdgcn_mfma_f32_32x32x16_bf16(kf[ds][1], qf[ds], ds == 0 ? z : N1, 0, 0, 0);
;         }
;     }
; #pragma unroll
;     for (int i = 0; i < 16; ++i) { l += C0[i]; l += C1[i]; }
;     bf16x8 pb[4];
;     { u32x4 w;
;       w.x = pk2(C0[0], C0[1]); w.y = pk2(C0[2], C0[3]); w.z = pk2(C0[4], C0[5]); w.w = pk2(C0[6], C0[7]); pb[0] = __builtin_bit_cast(bf16x8, w);
;       w.x = pk2(C0[8], C0[9]); w.y = pk2(C0[10], C0[11]); w.z = pk2(C0[12], C0[13]); w.w = pk2(C0[14], C0[15]); pb[1] = __builtin_bit_cast(bf16x8, w);
;       w.x = pk2(C1[0], C1[1]); w.y = pk2(C1[2], C1[3]); w.z = pk2(C1[4], C1[5]); w.w = pk2(C1[6], C1[7]); pb[2] = __builtin_bit_cast(bf16x8, w);
;       w.x = pk2(C1[8], C1[9]); w.y = pk2(C1[10], C1[11]); w.z = pk2(C1[12], C1[13]); w.w = pk2(C1[14], C1[15]); pb[3] = __builtin_bit_cast(bf16x8, w); }
;     if (HASNEXT) {
;         constexpr int VPER = (DK == 64) ? 6 : 4;
; #pragma unroll
	s_waitcnt vmcnt(0)
	ds_read_b128 v[80:83], v130
	s_waitcnt lgkmcnt(0)
	s_setprio 1
	ds_read_b128 v[48:51], v131 offset:17920
	ds_read_b128 v[124:127], v131 offset:17952
	ds_read_b128 v[182:185], v131 offset:13376
	ds_read_b128 v[186:189], v131 offset:17984
	ds_read_b128 v[190:193], v131 offset:13408
	ds_read_b128 v[194:197], v131 offset:18016
	ds_read_b64_tr_b16 v[110:111], v96 offset:26624
	ds_read_b64_tr_b16 v[112:113], v96 offset:28160
	ds_read_b64_tr_b16 v[106:107], v96 offset:26688
	s_waitcnt lgkmcnt(8)
	v_mfma_f32_32x32x16_bf16 v[48:63], v[48:51], v[76:79], 0
	v_add_co_u32_e32 v32, vcc, 0x20c000, v120
	ds_read_b64_tr_b16 v[108:109], v96 offset:28224
	s_nop 0
	v_addc_co_u32_e32 v33, vcc, 0, v121, vcc
	global_load_dwordx4 v[88:91], v[32:33], off
	v_add_co_u32_e32 v32, vcc, 0x208000, v118
	ds_read_b128 v[120:123], v131 offset:13344
	s_nop 0
	v_addc_co_u32_e32 v33, vcc, 0, v119, vcc
	global_load_dwordx4 v[92:95], v[32:33], off
	ds_read_b128 v[32:35], v131 offset:13312
	s_waitcnt lgkmcnt(0)
	v_mfma_f32_32x32x16_bf16 v[32:47], v[32:35], v[76:79], 0
	ds_read_b64_tr_b16 v[102:103], v96 offset:29696
	ds_read_b64_tr_b16 v[104:105], v96 offset:31232
	ds_read_b64_tr_b16 v[98:99], v96 offset:29760
	ds_read_b64_tr_b16 v[100:101], v96 offset:31296
	v_mfma_f32_32x32x16_bf16 v[32:47], v[120:123], v[72:75], v[32:47]
	v_add_f32_e32 v120, v146, v172
	v_add_f32_e32 v120, v132, v120
	v_cvt_pk_bf16_f32 v132, v132, v133
	v_add_f32_e32 v120, v148, v120
	v_add_f32_e32 v120, v133, v120
	v_cvt_pk_bf16_f32 v133, v134, v135
	v_add_f32_e32 v120, v158, v120
	v_add_f32_e32 v120, v134, v120
	v_cvt_pk_bf16_f32 v134, v136, v137
	v_add_f32_e32 v120, v159, v120
	v_add_f32_e32 v120, v135, v120
	v_cvt_pk_bf16_f32 v135, v139, v141
	v_mfma_f32_32x32x16_bf16 v[48:63], v[124:127], v[72:75], v[48:63]
	v_cvt_pk_bf16_f32 v124, v161, v163
	v_cvt_pk_bf16_f32 v125, v165, v168
	v_cvt_pk_bf16_f32 v126, v167, v169
	v_cvt_pk_bf16_f32 v127, v170, v171
	v_add_f32_e32 v120, v160, v120
	v_add_f32_e32 v120, v136, v120
	v_add_f32_e32 v120, v162, v120
	v_add_f32_e32 v120, v137, v120
	v_mfma_f32_32x32x16_bf16 v[32:47], v[182:185], v[68:71], v[32:47]
	v_add_f32_e32 v120, v164, v120
	v_add_f32_e32 v120, v139, v120
	v_add_f32_e32 v120, v166, v120
	v_add_f32_e32 v120, v141, v120
	v_add_f32_e32 v120, v161, v120
	v_add_f32_e32 v120, v138, v120
	v_cvt_pk_bf16_f32 v136, v138, v140
	v_mfma_f32_32x32x16_bf16 v[48:63], v[186:189], v[68:71], v[48:63]
	v_add_f32_e32 v120, v163, v120
	v_add_f32_e32 v120, v140, v120
	v_add_f32_e32 v120, v165, v120
	v_add_f32_e32 v120, v142, v120
	v_add_f32_e32 v120, v168, v120
	v_add_f32_e32 v120, v143, v120
	v_cvt_pk_bf16_f32 v137, v142, v143
	v_mfma_f32_32x32x16_bf16 v[32:47], v[190:193], v[64:67], v[32:47]
	v_add_f32_e32 v120, v167, v120
	v_add_f32_e32 v120, v144, v120
	v_add_f32_e32 v120, v169, v120
	v_add_f32_e32 v120, v145, v120
	v_add_f32_e32 v120, v170, v120
	v_add_f32_e32 v120, v147, v120
	v_cvt_pk_bf16_f32 v138, v144, v145
	v_mfma_f32_32x32x16_bf16 v[48:63], v[194:197], v[64:67], v[48:63]
	v_add_f32_e32 v120, v171, v120
	v_add_f32_e32 v128, v149, v120
	v_cvt_pk_bf16_f32 v120, v146, v148
	v_cvt_pk_bf16_f32 v121, v158, v159
	v_cvt_pk_bf16_f32 v122, v160, v162
	v_cvt_pk_bf16_f32 v123, v164, v166
	v_cvt_pk_bf16_f32 v139, v147, v149
	s_nop 0
	v_mfma_f32_32x32x16_bf16 v[16:31], v[110:113], v[120:123], v[16:31]
	ds_read_b64_tr_b16 v[110:111], v96 offset:32832
	ds_read_b64_tr_b16 v[112:113], v96 offset:34368
	v_exp_f32_e32 v140, v32
	v_exp_f32_e32 v141, v48
	v_exp_f32_e32 v142, v33
	v_exp_f32_e32 v143, v49
	v_exp_f32_e32 v144, v34
	v_mfma_f32_32x32x16_bf16 v[0:15], v[106:109], v[120:123], v[0:15]
	ds_read_b64_tr_b16 v[106:107], v96 offset:32768
	ds_read_b64_tr_b16 v[108:109], v96 offset:34304
	ds_read_b64_tr_b16 v[120:121], v96 offset:35904
	ds_read_b64_tr_b16 v[122:123], v96 offset:37440
	v_exp_f32_e32 v145, v50
	v_exp_f32_e32 v146, v35
	v_exp_f32_e32 v147, v51
	s_waitcnt lgkmcnt(8)
	v_mfma_f32_32x32x16_bf16 v[16:31], v[102:105], v[124:127], v[16:31]
	ds_read_b64_tr_b16 v[102:103], v96 offset:35840
	ds_read_b64_tr_b16 v[104:105], v96 offset:37376
	v_exp_f32_e32 v148, v36
	v_exp_f32_e32 v149, v52
	v_exp_f32_e32 v150, v37
	v_exp_f32_e32 v151, v53
	v_exp_f32_e32 v152, v38
	s_waitcnt lgkmcnt(8)
	v_mfma_f32_32x32x16_bf16 v[0:15], v[98:101], v[124:127], v[0:15]
	v_exp_f32_e32 v153, v54
	v_exp_f32_e32 v154, v39
	v_exp_f32_e32 v155, v55
	v_exp_f32_e32 v158, v40
	v_exp_f32_e32 v159, v58
	v_exp_f32_e32 v160, v43
	v_exp_f32_e32 v161, v59
	s_waitcnt lgkmcnt(4)
	v_mfma_f32_32x32x16_bf16 v[16:31], v[106:109], v[132:135], v[16:31]
	v_exp_f32_e32 v162, v44
	v_exp_f32_e32 v163, v60
	v_exp_f32_e32 v164, v45
	v_exp_f32_e32 v165, v61
	v_exp_f32_e32 v166, v46
	v_exp_f32_e32 v167, v62
	v_exp_f32_e32 v168, v47
	v_mfma_f32_32x32x16_bf16 v[0:15], v[110:113], v[132:135], v[0:15]
	v_exp_f32_e32 v132, v56
	v_exp_f32_e32 v133, v41
	v_exp_f32_e32 v134, v57
	v_exp_f32_e32 v135, v42
	v_exp_f32_e32 v169, v63
	s_waitcnt lgkmcnt(0)
	v_mfma_f32_32x32x16_bf16 v[16:31], v[102:105], v[136:139], v[16:31]
	v_mfma_f32_32x32x16_bf16 v[0:15], v[120:123], v[136:139], v[0:15]
	s_setprio 0
	s_waitcnt vmcnt(3)
	ds_write_b128 v130, v[80:83]
	s_waitcnt vmcnt(2)
	ds_write_b128 v117, v[84:87] offset:38912
	s_waitcnt lgkmcnt(0)
	s_barrier
; #define LAS __attribute__((address_space(3)))
; template <int DK, int PAR, bool HASNEXT, bool LDK, bool LDV, bool STK> ...
;     ...
;     LAS unsigned char* Kb = lds + ((PAR ^ 1) * A::KBUF);
;     LAS unsigned char* Vb = lds + 2 * A::KBUF + PAR * A::VBUF;
;     __builtin_amdgcn_s_setprio(1);
;     if (LDK) { ldk0 = *(const u32x4*)(kg0 + (size_t)(t + 3) * kstep); if (has1) ldk1 = *(const u32x4*)(kg1 + (size_t)(t + 3) * kstep); }
;     if (LDV) ldv = *(const u32x4*)(vg + (size_t)(t + 2) * vstep);
;     bf16x8 kf[A::NDS][2];
;     if (HASNEXT) {
; #pragma unroll
;         for (int ds = 0; ds < A::NDS; ++ds) {
;             kf[ds][0] = *(const LAS bf16x8*)(Kb + aoffk + ds * 32);
;             kf[ds][1] = *(const LAS bf16x8*)(Kb + aoffk + 32 * A::KSTR + ds * 32);
;         }
;     }
;     s16x4 vlo[4][2], vhi[4][2];
; #pragma unroll
;     for (int j = 0; j < 2; ++j) {
;         vlo[j][0] = vtr(Vb + aoffv + j * 16 * A::VSTR); vhi[j][0] = vtr(Vb + aoffv + (j * 16 + 8) * A::VSTR);
;         vlo[j][1] = vtr(Vb + aoffv + j * 16 * A::VSTR + 64); vhi[j][1] = vtr(Vb + aoffv + (j * 16 + 8) * A::VSTR + 64);
;     }
;     if (HASNEXT) {
;         f32x16 z;
; #pragma unroll
;         for (int i = 0; i < 16; ++i) z[i] = 0.f;
; #pragma unroll
;         for (int ds = 0; ds < A::NDS; ++ds) {
;             N0 = __builtin_amdgcn_mfma_f32_32x32x16_bf16(kf[ds][0], qf[ds], ds == 0 ? z : N0, 0, 0, 0);
;             N1 = __builtin_amdgcn_mfma_f32_32x32x16_bf16(kf[ds][1], qf[ds], ds == 0 ? z : N1, 0, 0, 0);
;         }
;     }
; #pragma unroll
;     for (int i = 0; i < 16; ++i) { l += C0[i]; l += C1[i]; }
;     bf16x8 pb[4];
;     { u32x4 w;
;       w.x = pk2(C0[0], C0[1]); w.y = pk2(C0[2], C0[3]); w.z = pk2(C0[4], C0[5]); w.w = pk2(C0[6], C0[7]); pb[0] = __builtin_bit_cast(bf16x8, w);
;       w.x = pk2(C0[8], C0[9]); w.y = pk2(C0[10], C0[11]); w.z = pk2(C0[12], C0[13]); w.w = pk2(C0[14], C0[15]); pb[1] = __builtin_bit_cast(bf16x8, w);
;       w.x = pk2(C1[0], C1[1]); w.y = pk2(C1[2], C1[3]); w.z = pk2(C1[4], C1[5]); w.w = pk2(C1[6], C1[7]); pb[2] = __builtin_bit_cast(bf16x8, w);
;       w.x = pk2(C1[8], C1[9]); w.y = pk2(C1[10], C1[11]); w.z = pk2(C1[12], C1[13]); w.w = pk2(C1[14], C1[15]); pb[3] = __builtin_bit_cast(bf16x8, w); }
;     if (HASNEXT) {
;         constexpr int VPER = (DK == 64) ? 6 : 4;
; #pragma unroll
	s_setprio 1
	ds_read_b128 v[32:35], v131
	s_mov_b32 s8, 0x20c000
	ds_read_b128 v[84:87], v131 offset:32
	ds_read_b128 v[98:101], v131 offset:4640
	ds_read_b128 v[102:105], v131 offset:64
	ds_read_b128 v[106:109], v131 offset:4672
	ds_read_b128 v[110:113], v131 offset:96
	ds_read_b64_tr_b16 v[122:123], v96 offset:38912
	ds_read_b64_tr_b16 v[124:125], v96 offset:40448
	s_waitcnt lgkmcnt(7)
	v_mfma_f32_32x32x16_bf16 v[32:47], v[32:35], v[76:79], 0
	v_add_co_u32_e32 v48, vcc, s8, v118
	v_add_f32_e32 v52, v140, v128
	s_nop 0
	v_addc_co_u32_e32 v49, vcc, 0, v119, vcc
	global_load_dwordx4 v[80:83], v[48:49], off
	ds_read_b128 v[48:51], v131 offset:4608
	v_add_f32_e32 v52, v141, v52
	v_add_f32_e32 v52, v142, v52
	v_add_f32_e32 v128, v143, v52
	s_waitcnt lgkmcnt(0)
	v_mfma_f32_32x32x16_bf16 v[48:63], v[48:51], v[76:79], 0
	v_add_f32_e32 v128, v144, v128
	v_add_f32_e32 v128, v145, v128
	v_add_f32_e32 v128, v146, v128
	v_add_f32_e32 v128, v147, v128
	v_add_f32_e32 v128, v148, v128
	v_add_f32_e32 v136, v149, v128
	ds_read_b128 v[118:121], v131 offset:4704
	v_mfma_f32_32x32x16_bf16 v[32:47], v[84:87], v[72:75], v[32:47]
	v_add_f32_e32 v84, v150, v136
	v_add_f32_e32 v84, v151, v84
	v_add_f32_e32 v84, v152, v84
	v_add_f32_e32 v84, v153, v84
	v_add_f32_e32 v84, v154, v84
	v_add_f32_e32 v86, v155, v84
	ds_read_b64_tr_b16 v[126:127], v96 offset:38976
	v_mfma_f32_32x32x16_bf16 v[48:63], v[98:101], v[72:75], v[48:63]
	v_add_f32_e32 v86, v158, v86
	v_add_f32_e32 v86, v132, v86
	v_add_f32_e32 v86, v133, v86
	v_add_f32_e32 v86, v134, v86
	v_add_f32_e32 v86, v135, v86
	v_add_f32_e32 v98, v159, v86
	ds_read_b64_tr_b16 v[128:129], v96 offset:40512
	v_mfma_f32_32x32x16_bf16 v[32:47], v[102:105], v[68:71], v[32:47]
	v_add_f32_e32 v98, v160, v98
	v_add_f32_e32 v98, v161, v98
	v_add_f32_e32 v98, v162, v98
	v_add_f32_e32 v98, v163, v98
	v_add_f32_e32 v98, v164, v98
	v_add_f32_e32 v100, v165, v98
	ds_read_b64_tr_b16 v[84:85], v96 offset:41984
	v_mfma_f32_32x32x16_bf16 v[48:63], v[106:109], v[68:71], v[48:63]
	v_add_f32_e32 v100, v166, v100
	v_add_f32_e32 v100, v167, v100
	v_add_f32_e32 v100, v168, v100
	ds_read_b64_tr_b16 v[86:87], v96 offset:43520
	ds_read_b64_tr_b16 v[98:99], v96 offset:42048
	v_add_f32_e32 v136, v169, v100
	ds_read_b64_tr_b16 v[100:101], v96 offset:43584
	v_cvt_pk_bf16_f32 v102, v140, v142
	v_cvt_pk_bf16_f32 v103, v144, v146
	v_mfma_f32_32x32x16_bf16 v[32:47], v[110:113], v[64:67], v[32:47]
	v_cvt_pk_bf16_f32 v104, v148, v150
	v_cvt_pk_bf16_f32 v105, v152, v154
	v_cvt_pk_bf16_f32 v106, v158, v133
	v_cvt_pk_bf16_f32 v107, v135, v160
	v_cvt_pk_bf16_f32 v108, v162, v164
	v_cvt_pk_bf16_f32 v109, v166, v168
	s_waitcnt lgkmcnt(6)
	v_mfma_f32_32x32x16_bf16 v[48:63], v[118:121], v[64:67], v[48:63]
	v_cvt_pk_bf16_f32 v110, v141, v143
	v_cvt_pk_bf16_f32 v111, v145, v147
	v_cvt_pk_bf16_f32 v112, v149, v151
	v_cvt_pk_bf16_f32 v113, v153, v155
	v_cvt_pk_bf16_f32 v118, v132, v134
	v_cvt_pk_bf16_f32 v119, v159, v161
	v_cvt_pk_bf16_f32 v120, v163, v165
	v_cvt_pk_bf16_f32 v121, v167, v169
	v_mfma_f32_32x32x16_bf16 v[16:31], v[122:125], v[102:105], v[16:31]
	ds_read_b64_tr_b16 v[122:123], v96 offset:45120
	ds_read_b64_tr_b16 v[124:125], v96 offset:46656
	v_exp_f32_e32 v132, v32
	v_exp_f32_e32 v133, v48
	v_exp_f32_e32 v134, v33
	v_exp_f32_e32 v135, v49
	v_exp_f32_e32 v137, v34
	s_waitcnt lgkmcnt(6)
	v_mfma_f32_32x32x16_bf16 v[0:15], v[126:129], v[102:105], v[0:15]
	ds_read_b64_tr_b16 v[102:103], v96 offset:45056
	ds_read_b64_tr_b16 v[104:105], v96 offset:46592
	ds_read_b64_tr_b16 v[126:127], v96 offset:48192
	ds_read_b64_tr_b16 v[128:129], v96 offset:49728
	v_exp_f32_e32 v138, v50
	v_exp_f32_e32 v139, v35
	v_exp_f32_e32 v140, v51
	s_waitcnt lgkmcnt(8)
	v_mfma_f32_32x32x16_bf16 v[16:31], v[84:87], v[106:109], v[16:31]
	ds_read_b64_tr_b16 v[84:85], v96 offset:48128
	ds_read_b64_tr_b16 v[86:87], v96 offset:49664
	v_exp_f32_e32 v141, v36
	v_exp_f32_e32 v142, v52
	v_exp_f32_e32 v143, v37
	v_exp_f32_e32 v144, v53
	v_exp_f32_e32 v145, v38
	s_waitcnt lgkmcnt(8)
	v_mfma_f32_32x32x16_bf16 v[0:15], v[98:101], v[106:109], v[0:15]
	v_exp_f32_e32 v146, v54
	v_exp_f32_e32 v147, v39
	v_exp_f32_e32 v148, v55
	v_exp_f32_e32 v149, v40
	v_exp_f32_e32 v150, v58
	v_exp_f32_e32 v151, v43
	v_exp_f32_e32 v152, v59
	s_waitcnt lgkmcnt(4)
	v_mfma_f32_32x32x16_bf16 v[16:31], v[102:105], v[110:113], v[16:31]
	v_exp_f32_e32 v153, v44
	v_exp_f32_e32 v154, v60
	v_exp_f32_e32 v155, v45
	v_exp_f32_e32 v158, v61
	v_exp_f32_e32 v159, v46
	v_exp_f32_e32 v160, v62
	v_exp_f32_e32 v161, v47
	v_mfma_f32_32x32x16_bf16 v[0:15], v[122:125], v[110:113], v[0:15]
	v_exp_f32_e32 v122, v56
	v_exp_f32_e32 v123, v41
	v_exp_f32_e32 v124, v57
	v_exp_f32_e32 v125, v42
	v_exp_f32_e32 v162, v63
	s_waitcnt lgkmcnt(0)
	v_mfma_f32_32x32x16_bf16 v[16:31], v[84:87], v[118:121], v[16:31]
	v_mfma_f32_32x32x16_bf16 v[0:15], v[126:129], v[118:121], v[0:15]
	s_setprio 0
	s_waitcnt vmcnt(2)
	ds_write_b128 v130, v[88:91] offset:13312
	s_waitcnt vmcnt(1)
	ds_write_b128 v117, v[92:95] offset:26624
	s_waitcnt lgkmcnt(0)
	s_barrier
; #define LAS __attribute__((address_space(3)))
; template <int DK, int PAR, bool HASNEXT, bool LDK, bool LDV, bool STK> ...
;     ...
;     LAS unsigned char* Kb = lds + ((PAR ^ 1) * A::KBUF);
;     LAS unsigned char* Vb = lds + 2 * A::KBUF + PAR * A::VBUF;
;     __builtin_amdgcn_s_setprio(1);
;     if (LDK) { ldk0 = *(const u32x4*)(kg0 + (size_t)(t + 3) * kstep); if (has1) ldk1 = *(const u32x4*)(kg1 + (size_t)(t + 3) * kstep); }
;     if (LDV) ldv = *(const u32x4*)(vg + (size_t)(t + 2) * vstep);
;     bf16x8 kf[A::NDS][2];
;     if (HASNEXT) {
; #pragma unroll
;         for (int ds = 0; ds < A::NDS; ++ds) {
;             kf[ds][0] = *(const LAS bf16x8*)(Kb + aoffk + ds * 32);
;             kf[ds][1] = *(const LAS bf16x8*)(Kb + aoffk + 32 * A::KSTR + ds * 32);
;         }
;     }
;     s16x4 vlo[4][2], vhi[4][2];
; #pragma unroll
;     for (int j = 0; j < 2; ++j) {
;         vlo[j][0] = vtr(Vb + aoffv + j * 16 * A::VSTR); vhi[j][0] = vtr(Vb + aoffv + (j * 16 + 8) * A::VSTR);
;         vlo[j][1] = vtr(Vb + aoffv + j * 16 * A::VSTR + 64); vhi[j][1] = vtr(Vb + aoffv + (j * 16 + 8) * A::VSTR + 64);
;     }
;     if (HASNEXT) {
;         f32x16 z;
; #pragma unroll
;         for (int i = 0; i < 16; ++i) z[i] = 0.f;
; #pragma unroll
;         for (int ds = 0; ds < A::NDS; ++ds) {
;             N0 = __builtin_amdgcn_mfma_f32_32x32x16_bf16(kf[ds][0], qf[ds], ds == 0 ? z : N0, 0, 0, 0);
;             N1 = __builtin_amdgcn_mfma_f32_32x32x16_bf16(kf[ds][1], qf[ds], ds == 0 ? z : N1, 0, 0, 0);
;         }
;     }
; #pragma unroll
;     for (int i = 0; i < 16; ++i) { l += C0[i]; l += C1[i]; }
;     bf16x8 pb[4];
;     { u32x4 w;
;       w.x = pk2(C0[0], C0[1]); w.y = pk2(C0[2], C0[3]); w.z = pk2(C0[4], C0[5]); w.w = pk2(C0[6], C0[7]); pb[0] = __builtin_bit_cast(bf16x8, w);
;       w.x = pk2(C0[8], C0[9]); w.y = pk2(C0[10], C0[11]); w.z = pk2(C0[12], C0[13]); w.w = pk2(C0[14], C0[15]); pb[1] = __builtin_bit_cast(bf16x8, w);
;       w.x = pk2(C1[0], C1[1]); w.y = pk2(C1[2], C1[3]); w.z = pk2(C1[4], C1[5]); w.w = pk2(C1[6], C1[7]); pb[2] = __builtin_bit_cast(bf16x8, w);
;       w.x = pk2(C1[8], C1[9]); w.y = pk2(C1[10], C1[11]); w.z = pk2(C1[12], C1[13]); w.w = pk2(C1[14], C1[15]); pb[3] = __builtin_bit_cast(bf16x8, w); }
;     if (HASNEXT) {
;         constexpr int VPER = (DK == 64) ? 6 : 4;
; #pragma unroll
	s_setprio 1
	ds_read_b128 v[32:35], v131 offset:13312
	ds_read_b128 v[48:51], v131 offset:17920
	ds_read_b128 v[84:87], v131 offset:13344
	ds_read_b128 v[88:91], v131 offset:17952
	ds_read_b128 v[92:95], v131 offset:13376
	ds_read_b128 v[98:101], v131 offset:17984
	ds_read_b128 v[102:105], v131 offset:13408
	ds_read_b128 v[106:109], v131 offset:18016
	ds_read_b64_tr_b16 v[110:111], v96 offset:26624
	s_waitcnt lgkmcnt(8)
	v_mfma_f32_32x32x16_bf16 v[32:47], v[32:35], v[76:79], 0
	v_add_f32_e32 v52, v132, v136
	v_add_f32_e32 v52, v133, v52
	v_add_f32_e32 v52, v134, v52
	v_add_f32_e32 v52, v135, v52
	v_add_f32_e32 v52, v137, v52
	v_add_f32_e32 v118, v138, v52
	ds_read_b64_tr_b16 v[112:113], v96 offset:28160
	s_waitcnt lgkmcnt(8)
	v_mfma_f32_32x32x16_bf16 v[48:63], v[48:51], v[76:79], 0
	v_add_f32_e32 v78, v139, v118
	v_add_f32_e32 v78, v140, v78
	v_add_f32_e32 v78, v141, v78
	v_add_f32_e32 v78, v142, v78
	v_add_f32_e32 v78, v143, v78
	v_add_f32_e32 v118, v144, v78
	ds_read_b64_tr_b16 v[76:77], v96 offset:26688
	s_waitcnt lgkmcnt(8)
	v_mfma_f32_32x32x16_bf16 v[32:47], v[84:87], v[72:75], v[32:47]
	v_add_f32_e32 v84, v145, v118
	v_add_f32_e32 v84, v146, v84
	v_add_f32_e32 v84, v147, v84
	v_add_f32_e32 v84, v148, v84
	v_add_f32_e32 v84, v149, v84
	v_add_f32_e32 v84, v122, v84
	ds_read_b64_tr_b16 v[78:79], v96 offset:28224
	s_waitcnt lgkmcnt(8)
	v_mfma_f32_32x32x16_bf16 v[48:63], v[88:91], v[72:75], v[48:63]
	v_add_f32_e32 v74, v123, v84
	v_add_f32_e32 v74, v124, v74
	v_add_f32_e32 v74, v125, v74
	v_add_f32_e32 v74, v150, v74
	v_add_f32_e32 v74, v151, v74
	v_add_f32_e32 v84, v152, v74
	ds_read_b64_tr_b16 v[72:73], v96 offset:29696
	s_waitcnt lgkmcnt(8)
	v_mfma_f32_32x32x16_bf16 v[32:47], v[92:95], v[68:71], v[32:47]
	v_add_f32_e32 v84, v153, v84
	v_add_f32_e32 v84, v154, v84
	v_add_f32_e32 v84, v155, v84
	v_add_f32_e32 v84, v158, v84
	v_add_f32_e32 v84, v159, v84
	v_add_f32_e32 v84, v160, v84
	ds_read_b64_tr_b16 v[74:75], v96 offset:31232
	s_waitcnt lgkmcnt(8)
	v_mfma_f32_32x32x16_bf16 v[48:63], v[98:101], v[68:71], v[48:63]
	v_add_f32_e32 v70, v161, v84
	ds_read_b64_tr_b16 v[68:69], v96 offset:29760
	v_add_f32_e32 v118, v162, v70
	ds_read_b64_tr_b16 v[70:71], v96 offset:31296
	v_cvt_pk_bf16_f32 v84, v132, v134
	v_cvt_pk_bf16_f32 v85, v137, v139
	v_cvt_pk_bf16_f32 v86, v141, v143
	v_cvt_pk_bf16_f32 v87, v145, v147
	s_waitcnt lgkmcnt(9)
	v_mfma_f32_32x32x16_bf16 v[32:47], v[102:105], v[64:67], v[32:47]
	v_cvt_pk_bf16_f32 v88, v149, v123
	v_cvt_pk_bf16_f32 v89, v125, v151
	v_cvt_pk_bf16_f32 v90, v153, v155
	v_cvt_pk_bf16_f32 v91, v159, v161
	v_cvt_pk_bf16_f32 v92, v133, v135
	v_cvt_pk_bf16_f32 v93, v138, v140
	s_waitcnt lgkmcnt(8)
	v_mfma_f32_32x32x16_bf16 v[48:63], v[106:109], v[64:67], v[48:63]
	v_cvt_pk_bf16_f32 v94, v142, v144
	v_cvt_pk_bf16_f32 v95, v146, v148
	v_cvt_pk_bf16_f32 v64, v122, v124
	v_cvt_pk_bf16_f32 v65, v150, v152
	v_cvt_pk_bf16_f32 v66, v154, v158
	v_cvt_pk_bf16_f32 v67, v160, v162
	s_waitcnt lgkmcnt(6)
	v_mfma_f32_32x32x16_bf16 v[16:31], v[110:113], v[84:87], v[16:31]
	ds_read_b64_tr_b16 v[98:99], v96 offset:35904
	ds_read_b64_tr_b16 v[100:101], v96 offset:37440
	v_exp_f32_e32 v102, v32
	s_nop 0
	v_exp_f32_e32 v103, v48
	v_exp_f32_e32 v48, v33
	v_exp_f32_e32 v63, v63
	s_waitcnt lgkmcnt(6)
	v_mfma_f32_32x32x16_bf16 v[0:15], v[76:79], v[84:87], v[0:15]
	ds_read_b64_tr_b16 v[76:77], v96 offset:32768
	ds_read_b64_tr_b16 v[78:79], v96 offset:34304
	ds_read_b64_tr_b16 v[84:85], v96 offset:32832
	ds_read_b64_tr_b16 v[86:87], v96 offset:34368
	s_waitcnt lgkmcnt(8)
	v_mfma_f32_32x32x16_bf16 v[16:31], v[72:75], v[88:91], v[16:31]
	ds_read_b64_tr_b16 v[72:73], v96 offset:35840
	ds_read_b64_tr_b16 v[74:75], v96 offset:37376
	s_waitcnt lgkmcnt(8)
	v_mfma_f32_32x32x16_bf16 v[0:15], v[68:71], v[88:91], v[0:15]
	v_exp_f32_e32 v68, v49
	v_exp_f32_e32 v49, v34
	v_exp_f32_e32 v69, v50
	v_exp_f32_e32 v50, v35
	v_exp_f32_e32 v70, v51
	v_exp_f32_e32 v51, v36
	v_exp_f32_e32 v71, v52
	s_waitcnt lgkmcnt(4)
	v_mfma_f32_32x32x16_bf16 v[16:31], v[76:79], v[92:95], v[16:31]
	v_exp_f32_e32 v52, v37
	v_exp_f32_e32 v76, v53
	v_exp_f32_e32 v53, v38
	v_exp_f32_e32 v77, v54
	v_exp_f32_e32 v54, v39
	v_exp_f32_e32 v78, v55
	v_exp_f32_e32 v55, v40
	s_waitcnt lgkmcnt(2)
	v_mfma_f32_32x32x16_bf16 v[0:15], v[84:87], v[92:95], v[0:15]
	v_exp_f32_e32 v79, v56
	v_exp_f32_e32 v56, v41
	v_exp_f32_e32 v84, v57
	v_exp_f32_e32 v57, v42
	v_exp_f32_e32 v85, v58
	v_exp_f32_e32 v58, v43
	v_exp_f32_e32 v86, v59
	s_waitcnt lgkmcnt(0)
	v_mfma_f32_32x32x16_bf16 v[16:31], v[72:75], v[64:67], v[16:31]
	v_exp_f32_e32 v59, v44
	v_exp_f32_e32 v72, v60
	v_exp_f32_e32 v60, v45
	v_exp_f32_e32 v73, v61
	v_exp_f32_e32 v61, v46
	v_exp_f32_e32 v74, v62
	v_exp_f32_e32 v62, v47
	v_mfma_f32_32x32x16_bf16 v[0:15], v[98:101], v[64:67], v[0:15]
	s_setprio 0
	s_waitcnt vmcnt(0)
	ds_write_b128 v117, v[80:83] offset:38912
	s_waitcnt lgkmcnt(0)
	s_barrier
; template <int DK, int PAR, bool HASNEXT, bool LDK, bool LDV, bool STK> ...
;     ...
;     for (int i = 0; i < 16; ++i) { l += C0[i]; l += C1[i]; }
;     bf16x8 pb[4];
;     { u32x4 w;
;       w.x = pk2(C0[0], C0[1]); w.y = pk2(C0[2], C0[3]); w.z = pk2(C0[4], C0[5]); w.w = pk2(C0[6], C0[7]); pb[0] = __builtin_bit_cast(bf16x8, w);
;       w.x = pk2(C0[8], C0[9]); w.y = pk2(C0[10], C0[11]); w.z = pk2(C0[12], C0[13]); w.w = pk2(C0[14], C0[15]); pb[1] = __builtin_bit_cast(bf16x8, w);
;       w.x = pk2(C1[0], C1[1]); w.y = pk2(C1[2], C1[3]); w.z = pk2(C1[4], C1[5]); w.w = pk2(C1[6], C1[7]); pb[2] = __builtin_bit_cast(bf16x8, w);
;       w.x = pk2(C1[8], C1[9]); w.y = pk2(C1[10], C1[11]); w.z = pk2(C1[12], C1[13]); w.w = pk2(C1[14], C1[15]); pb[3] = __builtin_bit_cast(bf16x8, w); }
;     if (HASNEXT) {
;         constexpr int VPER = (DK == 64) ? 6 : 4;
; #pragma unroll
;         for (int g = 0; g < 2 * A::NDS; ++g) { __builtin_amdgcn_sched_group_barrier(0x008, 1, 0); __builtin_amdgcn_sched_group_barrier(0x002, VPER, 0); }
;     }
;     asm volatile("" : "+v"(l));
;     __builtin_amdgcn_sched_barrier(0);
; #pragma unroll
;     for (int j = 2; j < 4; ++j) {
;         vlo[j][0] = vtr(Vb + aoffv + j * 16 * A::VSTR); vhi[j][0] = vtr(Vb + aoffv + (j * 16 + 8) * A::VSTR);
;         vlo[j][1] = vtr(Vb + aoffv + j * 16 * A::VSTR + 64); vhi[j][1] = vtr(Vb + aoffv + (j * 16 + 8) * A::VSTR + 64);
;     }
; #pragma unroll
;     for (int j = 0; j < 4; ++j) {
;         const bf16x8 a0 = __builtin_shufflevector(vlo[j][0], vhi[j][0], 0, 1, 2, 3, 4, 5, 6, 7);
;         const bf16x8 a1 = __builtin_shufflevector(vlo[j][1], vhi[j][1], 0, 1, 2, 3, 4, 5, 6, 7);
;         o0 = __builtin_amdgcn_mfma_f32_32x32x16_bf16(a0, pb[j], o0, 0, 0, 0);
;         o1 = __builtin_amdgcn_mfma_f32_32x32x16_bf16(a1, pb[j], o1, 0, 0, 0);
;     }
;     if (HASNEXT) {
; #pragma unroll
;         for (int i = 0; i < 16; ++i) { N0[i] = __builtin_amdgcn_exp2f(N0[i]); N1[i] = __builtin_amdgcn_exp2f(N1[i]); }
; #pragma unroll
;         for (int g = 0; g < 8; ++g) { __builtin_amdgcn_sched_group_barrier(0x008, 1, 0); __builtin_amdgcn_sched_group_barrier(0x002, 4, 0); }
;     }
;     __builtin_amdgcn_sched_barrier(0);
;     __builtin_amdgcn_s_setprio(0);
;     if (STK) { LAS unsigned char* Kn = lds + PAR * A::KBUF; *(LAS u32x4*)(Kn + kl0) = stk0; if (has1) *(LAS u32x4*)(Kn + kl1) = stk1; }
	s_setprio 1
	v_add_f32_e32 v64, v102, v118
	v_add_f32_e32 v64, v103, v64
	v_add_f32_e32 v64, v48, v64
	v_add_f32_e32 v64, v68, v64
	v_add_f32_e32 v64, v49, v64
	v_add_f32_e32 v64, v69, v64
	v_add_f32_e32 v64, v50, v64
	v_add_f32_e32 v64, v70, v64
	v_add_f32_e32 v64, v51, v64
	v_add_f32_e32 v64, v71, v64
	v_add_f32_e32 v64, v52, v64
	v_add_f32_e32 v64, v76, v64
	v_add_f32_e32 v64, v53, v64
	v_add_f32_e32 v64, v77, v64
	v_add_f32_e32 v64, v54, v64
	v_add_f32_e32 v64, v78, v64
	v_add_f32_e32 v64, v55, v64
	v_add_f32_e32 v64, v79, v64
	v_add_f32_e32 v64, v56, v64
	v_add_f32_e32 v64, v84, v64
	v_add_f32_e32 v64, v57, v64
	v_add_f32_e32 v64, v85, v64
	v_add_f32_e32 v64, v58, v64
	v_add_f32_e32 v64, v86, v64
	v_add_f32_e32 v64, v59, v64
	v_add_f32_e32 v64, v72, v64
	v_add_f32_e32 v64, v60, v64
	v_add_f32_e32 v64, v73, v64
	ds_read_b64_tr_b16 v[32:33], v96 offset:38912
	ds_read_b64_tr_b16 v[34:35], v96 offset:40448
	ds_read_b64_tr_b16 v[38:39], v96 offset:40512
	ds_read_b64_tr_b16 v[36:37], v96 offset:38976
	ds_read_b64_tr_b16 v[40:41], v96 offset:41984
	ds_read_b64_tr_b16 v[42:43], v96 offset:43520
	ds_read_b64_tr_b16 v[46:47], v96 offset:43584
	ds_read_b64_tr_b16 v[44:45], v96 offset:42048
	v_add_f32_e32 v64, v61, v64
	v_add_f32_e32 v64, v74, v64
	v_add_f32_e32 v64, v62, v64
	v_add_f32_e32 v64, v63, v64
	v_cvt_pk_bf16_f32 v48, v102, v48
	v_cvt_pk_bf16_f32 v49, v49, v50
	v_cvt_pk_bf16_f32 v50, v51, v52
	v_cvt_pk_bf16_f32 v51, v53, v54
	v_cvt_pk_bf16_f32 v52, v55, v56
	v_cvt_pk_bf16_f32 v53, v57, v58
	v_cvt_pk_bf16_f32 v54, v59, v60
	v_cvt_pk_bf16_f32 v55, v61, v62
	v_cvt_pk_bf16_f32 v56, v103, v68
	v_cvt_pk_bf16_f32 v57, v69, v70
	v_cvt_pk_bf16_f32 v58, v71, v76
	v_cvt_pk_bf16_f32 v59, v77, v78
	v_cvt_pk_bf16_f32 v60, v79, v84
	v_cvt_pk_bf16_f32 v61, v85, v86
	v_cvt_pk_bf16_f32 v62, v72, v73
	v_cvt_pk_bf16_f32 v63, v74, v63
	s_waitcnt lgkmcnt(6)
	v_mfma_f32_32x32x16_bf16 v[16:31], v[32:35], v[48:51], v[16:31]
	ds_read_b64_tr_b16 v[32:33], v96 offset:45056
	ds_read_b64_tr_b16 v[34:35], v96 offset:46592
	s_waitcnt lgkmcnt(6)
	v_mfma_f32_32x32x16_bf16 v[0:15], v[36:39], v[48:51], v[0:15]
	ds_read_b64_tr_b16 v[38:39], v96 offset:46656
	ds_read_b64_tr_b16 v[36:37], v96 offset:45120
	s_waitcnt lgkmcnt(6)
	v_mfma_f32_32x32x16_bf16 v[16:31], v[40:43], v[52:55], v[16:31]
	s_waitcnt lgkmcnt(4)
	v_mfma_f32_32x32x16_bf16 v[0:15], v[44:47], v[52:55], v[0:15]
	s_waitcnt lgkmcnt(2)
	v_mfma_f32_32x32x16_bf16 v[16:31], v[32:35], v[56:59], v[16:31]
	ds_read_b64_tr_b16 v[32:33], v96 offset:48128
	ds_read_b64_tr_b16 v[34:35], v96 offset:49664
	s_waitcnt lgkmcnt(2)
	v_mfma_f32_32x32x16_bf16 v[0:15], v[36:39], v[56:59], v[0:15]
	ds_read_b64_tr_b16 v[38:39], v96 offset:49728
	ds_read_b64_tr_b16 v[36:37], v96 offset:48192
	s_waitcnt lgkmcnt(2)
	v_mfma_f32_32x32x16_bf16 v[16:31], v[32:35], v[60:63], v[16:31]
	s_waitcnt lgkmcnt(0)
	v_mfma_f32_32x32x16_bf16 v[0:15], v[36:39], v[60:63], v[0:15]
	s_setprio 0
	v_mov_b32_e32 v32, v64
	s_nop 1
	v_permlane32_swap_b32_e32 v64, v32
	v_add_f32_e32 v32, v64, v32
	v_div_scale_f32 v33, s[8:9], v32, v32, 1.0
	v_rcp_f32_e32 v34, v33
	v_lshlrev_b32_e32 v96, 1, v116
	s_waitcnt lgkmcnt(0)
	s_barrier
	v_fma_f32 v35, -v33, v34, 1.0
	v_fmac_f32_e32 v34, v35, v34
	v_div_scale_f32 v35, vcc, 1.0, v32, 1.0
	v_mul_f32_e32 v36, v35, v34
	v_fma_f32 v37, -v33, v36, v35
	v_fmac_f32_e32 v36, v37, v34
	v_fma_f32 v33, -v33, v36, v35
	v_div_fmas_f32 v33, v33, v34, v36
	v_div_fixup_f32 v32, v33, v32, 1.0
	v_pk_mul_f32 v[16:17], v[16:17], v[32:33] op_sel_hi:[1,0]
	v_pk_mul_f32 v[18:19], v[18:19], v[32:33] op_sel_hi:[1,0]
	v_pk_mul_f32 v[0:1], v[0:1], v[32:33] op_sel_hi:[1,0]
	v_pk_mul_f32 v[2:3], v[2:3], v[32:33] op_sel_hi:[1,0]
	v_lshlrev_b64 v[34:35], 11, v[114:115]
	v_cvt_pk_bf16_f32 v16, v16, v17
	v_cvt_pk_bf16_f32 v17, v18, v19
	v_pk_mul_f32 v[18:19], v[20:21], v[32:33] op_sel_hi:[1,0]
	v_pk_mul_f32 v[20:21], v[22:23], v[32:33] op_sel_hi:[1,0]
	v_cvt_pk_bf16_f32 v0, v0, v1
	v_cvt_pk_bf16_f32 v1, v2, v3
	v_pk_mul_f32 v[2:3], v[4:5], v[32:33] op_sel_hi:[1,0]
	v_pk_mul_f32 v[4:5], v[6:7], v[32:33] op_sel_hi:[1,0]
	v_lshl_add_u64 v[34:35], s[6:7], 0, v[34:35]
	v_cvt_pk_bf16_f32 v18, v18, v19
	v_cvt_pk_bf16_f32 v19, v20, v21
	v_cvt_pk_bf16_f32 v2, v2, v3
	v_cvt_pk_bf16_f32 v3, v4, v5
	v_lshl_add_u64 v[34:35], v[34:35], 0, v[96:97]
	v_permlane32_swap_b32_e32 v16, v18
	v_permlane32_swap_b32_e32 v17, v19
	v_permlane32_swap_b32_e32 v0, v2
	v_permlane32_swap_b32_e32 v1, v3
	global_store_dwordx4 v[34:35], v[16:19], off
	global_store_dwordx4 v[34:35], v[0:3], off offset:64
	v_pk_mul_f32 v[20:21], v[30:31], v[32:33] op_sel_hi:[1,0]
	v_pk_mul_f32 v[16:17], v[24:25], v[32:33] op_sel_hi:[1,0]
	v_pk_mul_f32 v[18:19], v[26:27], v[32:33] op_sel_hi:[1,0]
	v_pk_mul_f32 v[0:1], v[8:9], v[32:33] op_sel_hi:[1,0]
	v_pk_mul_f32 v[2:3], v[10:11], v[32:33] op_sel_hi:[1,0]
	v_cvt_pk_bf16_f32 v16, v16, v17
	v_cvt_pk_bf16_f32 v17, v18, v19
	v_pk_mul_f32 v[18:19], v[28:29], v[32:33] op_sel_hi:[1,0]
	v_cvt_pk_bf16_f32 v0, v0, v1
	v_cvt_pk_bf16_f32 v1, v2, v3
	v_pk_mul_f32 v[2:3], v[12:13], v[32:33] op_sel_hi:[1,0]
	v_pk_mul_f32 v[4:5], v[14:15], v[32:33] op_sel_hi:[1,0]
	v_cvt_pk_bf16_f32 v18, v18, v19
	v_cvt_pk_bf16_f32 v19, v20, v21
	v_cvt_pk_bf16_f32 v2, v2, v3
	v_cvt_pk_bf16_f32 v3, v4, v5
	v_permlane32_swap_b32_e32 v16, v18
	v_permlane32_swap_b32_e32 v17, v19
	v_permlane32_swap_b32_e32 v0, v2
	v_permlane32_swap_b32_e32 v1, v3
	global_store_dwordx4 v[34:35], v[16:19], off offset:32
	global_store_dwordx4 v[34:35], v[0:3], off offset:96
	s_branch .LBB0_740
